# P8 deferred-store dispatch moved behind the first eight ds_read_b128 of the iteration (runs in the LDS read shadow); on top of v126
# speedup vs baseline: 1.0006x; 1.0002x over previous
.LBB0_877:
	ds_read_b128 v[150:153], v147
	ds_read_b128 v[154:157], v147 offset:1024
	ds_read_b128 v[158:161], v147 offset:2048
	ds_read_b128 v[162:165], v147 offset:3072
	ds_read_b128 v[166:169], v148
	ds_read_b128 v[170:173], v148 offset:1024
	ds_read_b128 v[174:177], v148 offset:2048
	ds_read_b128 v[178:181], v148 offset:3072
	s_cmp_eq_u32 s100, 0
	s_cbranch_scc1 .Ldhs8_idle
	s_cmp_lt_i32 s61, 6
	s_cbranch_scc0 .Ldhs8_hi
	s_cmp_lt_i32 s61, 2
	s_cbranch_scc0 .Ldhs8_q1
	s_cmp_lt_i32 s61, 0
	s_cbranch_scc0 .Ldhs8_g9
	global_store_dwordx4 v255, v[226:229], s[16:17] sc1 nt
	s_branch .Ldhs8_done

.Ldhs8_done:
	s_add_u32 s38, s36, 0xfffc0080
	s_addc_u32 s39, s37, -1
	s_cmp_eq_u32 s61, 12
	s_cselect_b32 s41, s27, s39
	s_cselect_b32 s40, s57, s38
	s_cselect_b32 s39, s25, s60
	s_cselect_b32 s38, s58, s59
	v_lshl_add_u64 v[214:215], s[36:37], 0, v[136:137]
	s_add_i32 m0, s35, 0xc000
	ds_read_b128 v[182:185], v149
	ds_read_b128 v[186:189], v149 offset:1024
	ds_read_b128 v[190:193], v149 offset:2048
	ds_read_b128 v[194:197], v149 offset:3072
	ds_read_b128 v[198:201], v149 offset:4096
	ds_read_b128 v[202:205], v149 offset:5120
	ds_read_b128 v[206:209], v149 offset:6144
	ds_read_b128 v[210:213], v149 offset:7168
	global_load_lds_dwordx4 v[214:215], off
	v_lshl_add_u64 v[214:215], s[36:37], 0, v[138:139]
	s_add_i32 m0, s35, 0xe000
	s_nop 0
	global_load_lds_dwordx4 v[214:215], off
	s_waitcnt vmcnt(9)
	s_waitcnt lgkmcnt(0)
	s_barrier
	s_setprio 1
	s_waitcnt lgkmcnt(0)
	v_mfma_f32_16x16x32_bf16 v[124:127], v[150:153], v[182:185], v[124:127]
	v_mfma_f32_16x16x32_bf16 v[120:123], v[158:161], v[182:185], v[120:123]
	v_mfma_f32_16x16x32_bf16 v[108:111], v[150:153], v[190:193], v[108:111]
	v_mfma_f32_16x16x32_bf16 v[104:107], v[158:161], v[190:193], v[104:107]
	v_mfma_f32_16x16x32_bf16 v[92:95], v[150:153], v[198:201], v[92:95]
	v_mfma_f32_16x16x32_bf16 v[88:91], v[158:161], v[198:201], v[88:91]
	v_mfma_f32_16x16x32_bf16 v[76:79], v[150:153], v[206:209], v[76:79]
	v_mfma_f32_16x16x32_bf16 v[72:75], v[158:161], v[206:209], v[72:75]
	v_mfma_f32_16x16x32_bf16 v[124:127], v[154:157], v[186:189], v[124:127]
	v_mfma_f32_16x16x32_bf16 v[120:123], v[162:165], v[186:189], v[120:123]
	v_mfma_f32_16x16x32_bf16 v[108:111], v[154:157], v[194:197], v[108:111]
	v_mfma_f32_16x16x32_bf16 v[104:107], v[162:165], v[194:197], v[104:107]
	v_mfma_f32_16x16x32_bf16 v[92:95], v[154:157], v[202:205], v[92:95]
	v_mfma_f32_16x16x32_bf16 v[88:91], v[162:165], v[202:205], v[88:91]
	v_mfma_f32_16x16x32_bf16 v[76:79], v[154:157], v[210:213], v[76:79]
	v_mfma_f32_16x16x32_bf16 v[72:75], v[162:165], v[210:213], v[72:75]
	s_setprio 0
	s_setprio 1
	v_mfma_f32_16x16x32_bf16 v[116:119], v[166:169], v[182:185], v[116:119]
	v_mfma_f32_16x16x32_bf16 v[112:115], v[174:177], v[182:185], v[112:115]
	v_mfma_f32_16x16x32_bf16 v[100:103], v[166:169], v[190:193], v[100:103]
	v_mfma_f32_16x16x32_bf16 v[96:99], v[174:177], v[190:193], v[96:99]
	v_mfma_f32_16x16x32_bf16 v[84:87], v[166:169], v[198:201], v[84:87]
	v_mfma_f32_16x16x32_bf16 v[80:83], v[174:177], v[198:201], v[80:83]
	v_mfma_f32_16x16x32_bf16 v[68:71], v[166:169], v[206:209], v[68:71]
	v_mfma_f32_16x16x32_bf16 v[64:67], v[174:177], v[206:209], v[64:67]
	v_mfma_f32_16x16x32_bf16 v[116:119], v[170:173], v[186:189], v[116:119]
	v_mfma_f32_16x16x32_bf16 v[112:115], v[178:181], v[186:189], v[112:115]
	v_mfma_f32_16x16x32_bf16 v[100:103], v[170:173], v[194:197], v[100:103]
	v_mfma_f32_16x16x32_bf16 v[96:99], v[178:181], v[194:197], v[96:99]
	v_mfma_f32_16x16x32_bf16 v[84:87], v[170:173], v[202:205], v[84:87]
	v_mfma_f32_16x16x32_bf16 v[80:83], v[178:181], v[202:205], v[80:83]
	v_mfma_f32_16x16x32_bf16 v[68:71], v[170:173], v[210:213], v[68:71]
	v_mfma_f32_16x16x32_bf16 v[64:67], v[178:181], v[210:213], v[64:67]
	s_setprio 0
	s_barrier
	s_add_i32 s62, s50, s3
	v_lshl_add_u64 v[214:215], s[38:39], 0, v[130:131]
	s_mov_b32 m0, s62
	ds_read_b128 v[182:185], v149 offset:16384
	ds_read_b128 v[186:189], v149 offset:17408
	ds_read_b128 v[190:193], v149 offset:18432
	ds_read_b128 v[194:197], v149 offset:19456
	ds_read_b128 v[198:201], v149 offset:20480
	ds_read_b128 v[202:205], v149 offset:21504
	ds_read_b128 v[206:209], v149 offset:22528
	ds_read_b128 v[210:213], v149 offset:23552
	global_load_lds_dwordx4 v[214:215], off
	s_add_i32 m0, s62, 0x2000
	s_add_u32 s62, s38, 0x40000
	v_lshl_add_u64 v[216:217], s[38:39], 0, v[134:135]
	s_addc_u32 s63, s39, 0
	s_add_i32 s64, s51, s3
	global_load_lds_dwordx4 v[216:217], off
	v_lshl_add_u64 v[218:219], s[62:63], 0, v[130:131]
	s_mov_b32 m0, s64
	v_lshl_add_u64 v[222:223], s[40:41], 0, v[132:133]
	global_load_lds_dwordx4 v[218:219], off
	v_lshl_add_u64 v[218:219], s[62:63], 0, v[134:135]
	s_add_i32 m0, s64, 0x2000
	s_nop 0
	global_load_lds_dwordx4 v[218:219], off
	v_lshl_add_u64 v[218:219], s[40:41], 0, v[128:129]
	s_mov_b32 m0, s35
	s_nop 0
	global_load_lds_dwordx4 v[218:219], off
	s_mov_b32 m0, s42
	s_nop 0
	global_load_lds_dwordx4 v[222:223], off
	s_waitcnt vmcnt(9)
	s_waitcnt lgkmcnt(0)
	s_barrier
	s_setprio 1
	s_waitcnt lgkmcnt(0)
	v_mfma_f32_16x16x32_bf16 v[60:63], v[150:153], v[182:185], v[60:63]
	v_mfma_f32_16x16x32_bf16 v[56:59], v[158:161], v[182:185], v[56:59]
	v_mfma_f32_16x16x32_bf16 v[44:47], v[150:153], v[190:193], v[44:47]
	v_mfma_f32_16x16x32_bf16 v[40:43], v[158:161], v[190:193], v[40:43]
	v_mfma_f32_16x16x32_bf16 v[28:31], v[150:153], v[198:201], v[28:31]
	v_mfma_f32_16x16x32_bf16 v[24:27], v[158:161], v[198:201], v[24:27]
	v_mfma_f32_16x16x32_bf16 v[12:15], v[150:153], v[206:209], v[12:15]
	v_mfma_f32_16x16x32_bf16 v[8:11], v[158:161], v[206:209], v[8:11]
	v_mfma_f32_16x16x32_bf16 v[60:63], v[154:157], v[186:189], v[60:63]
	v_mfma_f32_16x16x32_bf16 v[56:59], v[162:165], v[186:189], v[56:59]
	v_mfma_f32_16x16x32_bf16 v[44:47], v[154:157], v[194:197], v[44:47]
	v_mfma_f32_16x16x32_bf16 v[40:43], v[162:165], v[194:197], v[40:43]
	v_mfma_f32_16x16x32_bf16 v[28:31], v[154:157], v[202:205], v[28:31]
	v_mfma_f32_16x16x32_bf16 v[24:27], v[162:165], v[202:205], v[24:27]
	v_mfma_f32_16x16x32_bf16 v[12:15], v[154:157], v[210:213], v[12:15]
	v_mfma_f32_16x16x32_bf16 v[8:11], v[162:165], v[210:213], v[8:11]
	s_setprio 0
	s_setprio 1
	v_mfma_f32_16x16x32_bf16 v[52:55], v[166:169], v[182:185], v[52:55]
	v_mfma_f32_16x16x32_bf16 v[48:51], v[174:177], v[182:185], v[48:51]
	v_mfma_f32_16x16x32_bf16 v[36:39], v[166:169], v[190:193], v[36:39]
	v_mfma_f32_16x16x32_bf16 v[32:35], v[174:177], v[190:193], v[32:35]
	v_mfma_f32_16x16x32_bf16 v[20:23], v[166:169], v[198:201], v[20:23]
	v_mfma_f32_16x16x32_bf16 v[16:19], v[174:177], v[198:201], v[16:19]
	v_mfma_f32_16x16x32_bf16 v[4:7], v[166:169], v[206:209], v[4:7]
	v_mfma_f32_16x16x32_bf16 v[0:3], v[174:177], v[206:209], v[0:3]
	v_mfma_f32_16x16x32_bf16 v[52:55], v[170:173], v[186:189], v[52:55]
	v_mfma_f32_16x16x32_bf16 v[48:51], v[178:181], v[186:189], v[48:51]
	v_mfma_f32_16x16x32_bf16 v[36:39], v[170:173], v[194:197], v[36:39]
	v_mfma_f32_16x16x32_bf16 v[32:35], v[178:181], v[194:197], v[32:35]
	v_mfma_f32_16x16x32_bf16 v[20:23], v[170:173], v[202:205], v[20:23]
	v_mfma_f32_16x16x32_bf16 v[16:19], v[178:181], v[202:205], v[16:19]
	v_mfma_f32_16x16x32_bf16 v[4:7], v[170:173], v[210:213], v[4:7]
	v_mfma_f32_16x16x32_bf16 v[0:3], v[178:181], v[210:213], v[0:3]
	s_setprio 0
	s_barrier
	s_add_i32 s62, 0, 0x18000
	s_add_i32 s63, 0, 0x1c000
	v_add_u32_e32 v162, s62, v145
	v_add_u32_e32 v178, s63, v145
	ds_read_b128 v[150:153], v162
	ds_read_b128 v[154:157], v162 offset:1024
	ds_read_b128 v[158:161], v162 offset:2048
	ds_read_b128 v[162:165], v162 offset:3072
	ds_read_b128 v[166:169], v178
	ds_read_b128 v[170:173], v178 offset:1024
	ds_read_b128 v[174:177], v178 offset:2048
	ds_read_b128 v[178:181], v178 offset:3072
	s_add_u32 s40, s40, 0x40000
	s_addc_u32 s41, s41, 0
	s_mov_b32 m0, s43
	v_lshl_add_u64 v[224:225], s[40:41], 0, v[128:129]
	ds_read_b128 v[182:185], v149 offset:32768
	ds_read_b128 v[186:189], v149 offset:33792
	ds_read_b128 v[190:193], v149 offset:34816
	ds_read_b128 v[194:197], v149 offset:35840
	ds_read_b128 v[198:201], v149 offset:36864
	ds_read_b128 v[202:205], v149 offset:37888
	ds_read_b128 v[206:209], v149 offset:38912
	ds_read_b128 v[210:213], v149 offset:39936
	global_load_lds_dwordx4 v[224:225], off
	v_lshl_add_u64 v[224:225], s[40:41], 0, v[132:133]
	s_mov_b32 m0, s44
	s_nop 0
	global_load_lds_dwordx4 v[224:225], off
	s_waitcnt vmcnt(8)
	s_waitcnt lgkmcnt(0)
	s_barrier
	s_setprio 1
	s_waitcnt lgkmcnt(0)
	v_mfma_f32_16x16x32_bf16 v[124:127], v[150:153], v[182:185], v[124:127]
	v_mfma_f32_16x16x32_bf16 v[120:123], v[158:161], v[182:185], v[120:123]
	v_mfma_f32_16x16x32_bf16 v[108:111], v[150:153], v[190:193], v[108:111]
	v_mfma_f32_16x16x32_bf16 v[104:107], v[158:161], v[190:193], v[104:107]
	v_mfma_f32_16x16x32_bf16 v[92:95], v[150:153], v[198:201], v[92:95]
	v_mfma_f32_16x16x32_bf16 v[88:91], v[158:161], v[198:201], v[88:91]
	v_mfma_f32_16x16x32_bf16 v[76:79], v[150:153], v[206:209], v[76:79]
	v_mfma_f32_16x16x32_bf16 v[72:75], v[158:161], v[206:209], v[72:75]
	v_mfma_f32_16x16x32_bf16 v[124:127], v[154:157], v[186:189], v[124:127]
	v_mfma_f32_16x16x32_bf16 v[120:123], v[162:165], v[186:189], v[120:123]
	v_mfma_f32_16x16x32_bf16 v[108:111], v[154:157], v[194:197], v[108:111]
	v_mfma_f32_16x16x32_bf16 v[104:107], v[162:165], v[194:197], v[104:107]
	v_mfma_f32_16x16x32_bf16 v[92:95], v[154:157], v[202:205], v[92:95]
	v_mfma_f32_16x16x32_bf16 v[88:91], v[162:165], v[202:205], v[88:91]
	v_mfma_f32_16x16x32_bf16 v[76:79], v[154:157], v[210:213], v[76:79]
	v_mfma_f32_16x16x32_bf16 v[72:75], v[162:165], v[210:213], v[72:75]
	s_setprio 0
	s_setprio 1
	v_mfma_f32_16x16x32_bf16 v[116:119], v[166:169], v[182:185], v[116:119]
	v_mfma_f32_16x16x32_bf16 v[112:115], v[174:177], v[182:185], v[112:115]
	v_mfma_f32_16x16x32_bf16 v[100:103], v[166:169], v[190:193], v[100:103]
	v_mfma_f32_16x16x32_bf16 v[96:99], v[174:177], v[190:193], v[96:99]
	v_mfma_f32_16x16x32_bf16 v[84:87], v[166:169], v[198:201], v[84:87]
	v_mfma_f32_16x16x32_bf16 v[80:83], v[174:177], v[198:201], v[80:83]
	v_mfma_f32_16x16x32_bf16 v[68:71], v[166:169], v[206:209], v[68:71]
	v_mfma_f32_16x16x32_bf16 v[64:67], v[174:177], v[206:209], v[64:67]
	v_mfma_f32_16x16x32_bf16 v[116:119], v[170:173], v[186:189], v[116:119]
	v_mfma_f32_16x16x32_bf16 v[112:115], v[178:181], v[186:189], v[112:115]
	v_mfma_f32_16x16x32_bf16 v[100:103], v[170:173], v[194:197], v[100:103]
	v_mfma_f32_16x16x32_bf16 v[96:99], v[178:181], v[194:197], v[96:99]
	v_mfma_f32_16x16x32_bf16 v[84:87], v[170:173], v[202:205], v[84:87]
	v_mfma_f32_16x16x32_bf16 v[80:83], v[178:181], v[202:205], v[80:83]
	v_mfma_f32_16x16x32_bf16 v[68:71], v[170:173], v[210:213], v[68:71]
	v_mfma_f32_16x16x32_bf16 v[64:67], v[178:181], v[210:213], v[64:67]
	s_setprio 0
	s_barrier
	s_add_i32 s40, s62, s3
	v_lshl_add_u64 v[214:215], v[214:215], 0, s[12:13]
	s_mov_b32 m0, s40
	ds_read_b128 v[182:185], v149 offset:49152
	ds_read_b128 v[186:189], v149 offset:50176
	ds_read_b128 v[190:193], v149 offset:51200
	ds_read_b128 v[194:197], v149 offset:52224
	ds_read_b128 v[198:201], v149 offset:53248
	ds_read_b128 v[202:205], v149 offset:54272
	ds_read_b128 v[206:209], v149 offset:55296
	ds_read_b128 v[210:213], v149 offset:56320
	global_load_lds_dwordx4 v[214:215], off
	s_add_i32 m0, s40, 0x2000
	s_add_u32 s38, s38, 0x40080
	v_lshl_add_u64 v[214:215], v[216:217], 0, s[12:13]
	s_addc_u32 s39, s39, 0
	s_add_i32 s40, s63, s3
	global_load_lds_dwordx4 v[214:215], off
	v_lshl_add_u64 v[214:215], s[38:39], 0, v[130:131]
	s_mov_b32 m0, s40
	s_nop 0
	global_load_lds_dwordx4 v[214:215], off
	v_lshl_add_u64 v[214:215], s[38:39], 0, v[134:135]
	s_add_i32 m0, s40, 0x2000
	s_nop 0
	global_load_lds_dwordx4 v[214:215], off
	v_lshl_add_u64 v[214:215], v[218:219], 0, s[12:13]
	s_mov_b32 m0, s47
	s_nop 0
	global_load_lds_dwordx4 v[214:215], off
	v_lshl_add_u64 v[214:215], v[222:223], 0, s[12:13]
	s_mov_b32 m0, s48
	s_nop 0
	global_load_lds_dwordx4 v[214:215], off
	s_waitcnt vmcnt(8)
	s_waitcnt lgkmcnt(0)
	s_barrier
	s_setprio 1
	s_waitcnt lgkmcnt(0)
	v_mfma_f32_16x16x32_bf16 v[60:63], v[150:153], v[182:185], v[60:63]
	v_mfma_f32_16x16x32_bf16 v[56:59], v[158:161], v[182:185], v[56:59]
	v_mfma_f32_16x16x32_bf16 v[44:47], v[150:153], v[190:193], v[44:47]
	v_mfma_f32_16x16x32_bf16 v[40:43], v[158:161], v[190:193], v[40:43]
	v_mfma_f32_16x16x32_bf16 v[28:31], v[150:153], v[198:201], v[28:31]
	v_mfma_f32_16x16x32_bf16 v[24:27], v[158:161], v[198:201], v[24:27]
	v_mfma_f32_16x16x32_bf16 v[12:15], v[150:153], v[206:209], v[12:15]
	v_mfma_f32_16x16x32_bf16 v[8:11], v[158:161], v[206:209], v[8:11]
	v_mfma_f32_16x16x32_bf16 v[60:63], v[154:157], v[186:189], v[60:63]
	v_mfma_f32_16x16x32_bf16 v[56:59], v[162:165], v[186:189], v[56:59]
	v_mfma_f32_16x16x32_bf16 v[44:47], v[154:157], v[194:197], v[44:47]
	v_mfma_f32_16x16x32_bf16 v[40:43], v[162:165], v[194:197], v[40:43]
	v_mfma_f32_16x16x32_bf16 v[28:31], v[154:157], v[202:205], v[28:31]
	v_mfma_f32_16x16x32_bf16 v[24:27], v[162:165], v[202:205], v[24:27]
	v_mfma_f32_16x16x32_bf16 v[12:15], v[154:157], v[210:213], v[12:15]
	v_mfma_f32_16x16x32_bf16 v[8:11], v[162:165], v[210:213], v[8:11]
	s_setprio 0
	s_setprio 1
	v_mfma_f32_16x16x32_bf16 v[52:55], v[166:169], v[182:185], v[52:55]
	v_mfma_f32_16x16x32_bf16 v[48:51], v[174:177], v[182:185], v[48:51]
	v_mfma_f32_16x16x32_bf16 v[36:39], v[166:169], v[190:193], v[36:39]
	v_mfma_f32_16x16x32_bf16 v[32:35], v[174:177], v[190:193], v[32:35]
	v_mfma_f32_16x16x32_bf16 v[20:23], v[166:169], v[198:201], v[20:23]
	v_mfma_f32_16x16x32_bf16 v[16:19], v[174:177], v[198:201], v[16:19]
	v_mfma_f32_16x16x32_bf16 v[4:7], v[166:169], v[206:209], v[4:7]
	v_mfma_f32_16x16x32_bf16 v[0:3], v[174:177], v[206:209], v[0:3]
	v_mfma_f32_16x16x32_bf16 v[52:55], v[170:173], v[186:189], v[52:55]
	v_mfma_f32_16x16x32_bf16 v[48:51], v[178:181], v[186:189], v[48:51]
	v_mfma_f32_16x16x32_bf16 v[36:39], v[170:173], v[194:197], v[36:39]
	v_mfma_f32_16x16x32_bf16 v[32:35], v[178:181], v[194:197], v[32:35]
	v_mfma_f32_16x16x32_bf16 v[20:23], v[170:173], v[202:205], v[20:23]
	v_mfma_f32_16x16x32_bf16 v[16:19], v[178:181], v[202:205], v[16:19]
	v_mfma_f32_16x16x32_bf16 v[4:7], v[170:173], v[210:213], v[4:7]
	v_mfma_f32_16x16x32_bf16 v[0:3], v[178:181], v[210:213], v[0:3]
	s_setprio 0
	s_barrier
	s_add_i32 s61, s61, 2
	s_add_u32 s36, s36, 0x100
	s_addc_u32 s37, s37, 0
	s_add_u32 s59, s59, 0x100
	s_addc_u32 s60, s60, 0
	s_cmp_gt_u32 s61, 13
	s_cbranch_scc0 .LBB0_877
	s_and_b64 vcc, exec, s[14:15]
	s_cbranch_vccz .LBB0_880
	s_barrier
